# v3 plus: software-pipelined (double-buffered) K-loop of the down-projection meta-row item in gemm3's tail (WGs 220-255 were the pole of gemm3 by ~20-35 us in layers 0-2)
# speedup vs baseline: 1.0062x; 1.0000x over previous
; #define SCHED __builtin_amdgcn_sched_barrier(0)
; template <class Epi>
; DEV void skinny_item(LAS unsigned char* lds, const bf16_t* __restrict__ A, int lda, const bf16_t* __restrict__ B, int ldb, int K, int mb, int pn, const Epi& epi) {
;     ...
;     const int nsteps = K >> 5;
; #pragma unroll 1
;     for (int st = wid; st < nsteps; st += 8) {
;         const int k0 = st * 32;
;         const bf16x8 a = *(const bf16x8*)(ap + k0);
;         bf16x8 b[16];
; #pragma unroll
;         for (int nb = 0; nb < 16; ++nb) b[nb] = *(const bf16x8*)(bp + nb * b16 + k0);
;         SCHED;
; #pragma unroll
;         for (int nb = 0; nb < 16; ++nb) acc[nb] = __builtin_amdgcn_mfma_f32_16x16x32_bf16(b[nb], a, acc[nb], 0, 0, 0);
;         SCHED;
;     }
.LBB0_1365:
	s_movk_i32 s101, 10
	v_ashrrev_i32_e32 v69, 31, v68
	v_lshlrev_b64 v[74:75], 1, v[68:69]
	v_lshl_add_u64 v[138:139], v[64:65], 0, v[74:75]
	v_add_co_u32_e32 v82, vcc, s28, v138
	v_lshl_add_u64 v[76:77], v[66:67], 0, v[74:75]
	s_nop 0
	v_addc_co_u32_e32 v83, vcc, 0, v139, vcc
	v_add_co_u32_e32 v86, vcc, s29, v138
	global_load_dwordx4 v[74:77], v[76:77], off
	s_nop 0
	global_load_dwordx4 v[78:81], v[138:139], off
	v_addc_co_u32_e32 v87, vcc, 0, v139, vcc
	v_add_co_u32_e32 v90, vcc, s30, v138
	global_load_dwordx4 v[82:85], v[82:83], off
	s_nop 0
	global_load_dwordx4 v[86:89], v[86:87], off
	v_addc_co_u32_e32 v91, vcc, 0, v139, vcc
	v_add_co_u32_e32 v94, vcc, s19, v138
	s_nop 1
	v_addc_co_u32_e32 v95, vcc, 0, v139, vcc
	v_add_co_u32_e32 v98, vcc, s31, v138
	global_load_dwordx4 v[90:93], v[90:91], off
	s_nop 0
	global_load_dwordx4 v[94:97], v[94:95], off
	v_addc_co_u32_e32 v99, vcc, 0, v139, vcc
	v_add_co_u32_e32 v102, vcc, s34, v138
	s_nop 1
	v_addc_co_u32_e32 v103, vcc, 0, v139, vcc
	v_add_co_u32_e32 v106, vcc, s36, v138
	global_load_dwordx4 v[98:101], v[98:99], off
	s_nop 0
	global_load_dwordx4 v[102:105], v[102:103], off
	v_addc_co_u32_e32 v107, vcc, 0, v139, vcc
	v_add_co_u32_e32 v110, vcc, s37, v138
	s_nop 1
	v_addc_co_u32_e32 v111, vcc, 0, v139, vcc
	v_add_co_u32_e32 v114, vcc, s85, v138
	global_load_dwordx4 v[106:109], v[106:107], off
	s_nop 0
	global_load_dwordx4 v[110:113], v[110:111], off
	v_addc_co_u32_e32 v115, vcc, 0, v139, vcc
	v_add_co_u32_e32 v118, vcc, s78, v138
	s_nop 1
	v_addc_co_u32_e32 v119, vcc, 0, v139, vcc
	v_add_co_u32_e32 v122, vcc, s79, v138
	global_load_dwordx4 v[114:117], v[114:115], off
	s_nop 0
	global_load_dwordx4 v[118:121], v[118:119], off
	v_addc_co_u32_e32 v123, vcc, 0, v139, vcc
	v_add_co_u32_e32 v126, vcc, s90, v138
	s_nop 1
	v_addc_co_u32_e32 v127, vcc, 0, v139, vcc
	v_add_co_u32_e32 v130, vcc, s91, v138
	global_load_dwordx4 v[122:125], v[122:123], off
	s_nop 0
	global_load_dwordx4 v[126:129], v[126:127], off
	v_addc_co_u32_e32 v131, vcc, 0, v139, vcc
	v_add_co_u32_e32 v134, vcc, s60, v138
	s_nop 1
	v_addc_co_u32_e32 v135, vcc, 0, v139, vcc
	v_add_co_u32_e32 v138, vcc, s61, v138
	global_load_dwordx4 v[130:133], v[130:131], off
	s_nop 0
	global_load_dwordx4 v[134:137], v[134:135], off
	v_addc_co_u32_e32 v139, vcc, 0, v139, vcc
	global_load_dwordx4 v[138:141], v[138:139], off
.Ltl_loop:
	s_cmp_eq_u32 s101, 0
	s_cbranch_scc1 .Ltl_lastA
	s_sub_u32 s101, s101, 1
	v_add_u32_e32 v68, 0x100, v68
	v_ashrrev_i32_e32 v69, 31, v68
	v_lshlrev_b64 v[142:143], 1, v[68:69]
	v_lshl_add_u64 v[232:233], v[64:65], 0, v[142:143]
	v_add_co_u32_e32 v150, vcc, s28, v232
	v_lshl_add_u64 v[144:145], v[66:67], 0, v[142:143]
	s_nop 0
	v_addc_co_u32_e32 v151, vcc, 0, v233, vcc
	v_add_co_u32_e32 v154, vcc, s29, v232
	global_load_dwordx4 v[142:145], v[144:145], off
	s_nop 0
	global_load_dwordx4 v[146:149], v[232:233], off
	v_addc_co_u32_e32 v155, vcc, 0, v233, vcc
	v_add_co_u32_e32 v158, vcc, s30, v232
	global_load_dwordx4 v[150:153], v[150:151], off
	s_nop 0
	global_load_dwordx4 v[154:157], v[154:155], off
	v_addc_co_u32_e32 v159, vcc, 0, v233, vcc
	v_add_co_u32_e32 v162, vcc, s19, v232
	s_nop 1
	v_addc_co_u32_e32 v163, vcc, 0, v233, vcc
	v_add_co_u32_e32 v166, vcc, s31, v232
	global_load_dwordx4 v[158:161], v[158:159], off
	s_nop 0
	global_load_dwordx4 v[162:165], v[162:163], off
	v_addc_co_u32_e32 v167, vcc, 0, v233, vcc
	v_add_co_u32_e32 v170, vcc, s34, v232
	s_nop 1
	v_addc_co_u32_e32 v171, vcc, 0, v233, vcc
	v_add_co_u32_e32 v174, vcc, s36, v232
	global_load_dwordx4 v[166:169], v[166:167], off
	s_nop 0
	global_load_dwordx4 v[170:173], v[170:171], off
	v_addc_co_u32_e32 v175, vcc, 0, v233, vcc
	v_add_co_u32_e32 v178, vcc, s37, v232
	s_nop 1
	v_addc_co_u32_e32 v179, vcc, 0, v233, vcc
	v_add_co_u32_e32 v182, vcc, s85, v232
	global_load_dwordx4 v[174:177], v[174:175], off
	s_nop 0
	global_load_dwordx4 v[178:181], v[178:179], off
	v_addc_co_u32_e32 v183, vcc, 0, v233, vcc
	v_add_co_u32_e32 v212, vcc, s78, v232
	s_nop 1
	v_addc_co_u32_e32 v213, vcc, 0, v233, vcc
	v_add_co_u32_e32 v216, vcc, s79, v232
	global_load_dwordx4 v[182:185], v[182:183], off
	s_nop 0
	global_load_dwordx4 v[212:215], v[212:213], off
	v_addc_co_u32_e32 v217, vcc, 0, v233, vcc
	v_add_co_u32_e32 v220, vcc, s90, v232
	s_nop 1
	v_addc_co_u32_e32 v221, vcc, 0, v233, vcc
	v_add_co_u32_e32 v224, vcc, s91, v232
	global_load_dwordx4 v[216:219], v[216:217], off
	s_nop 0
	global_load_dwordx4 v[220:223], v[220:221], off
	v_addc_co_u32_e32 v225, vcc, 0, v233, vcc
	v_add_co_u32_e32 v228, vcc, s60, v232
	s_nop 1
	v_addc_co_u32_e32 v229, vcc, 0, v233, vcc
	v_add_co_u32_e32 v232, vcc, s61, v232
	global_load_dwordx4 v[224:227], v[224:225], off
	s_nop 0
	global_load_dwordx4 v[228:231], v[228:229], off
	v_addc_co_u32_e32 v233, vcc, 0, v233, vcc
	global_load_dwordx4 v[232:235], v[232:233], off
	s_waitcnt vmcnt(32)
	v_mfma_f32_16x16x32_bf16 v[60:63], v[78:81], v[74:77], v[60:63]
	s_waitcnt vmcnt(31)
	v_mfma_f32_16x16x32_bf16 v[56:59], v[82:85], v[74:77], v[56:59]
	s_waitcnt vmcnt(30)
	v_mfma_f32_16x16x32_bf16 v[52:55], v[86:89], v[74:77], v[52:55]
	s_waitcnt vmcnt(29)
	v_mfma_f32_16x16x32_bf16 v[48:51], v[90:93], v[74:77], v[48:51]
	s_waitcnt vmcnt(28)
	v_mfma_f32_16x16x32_bf16 v[44:47], v[94:97], v[74:77], v[44:47]
	s_waitcnt vmcnt(27)
	v_mfma_f32_16x16x32_bf16 v[40:43], v[98:101], v[74:77], v[40:43]
	s_waitcnt vmcnt(26)
	v_mfma_f32_16x16x32_bf16 v[36:39], v[102:105], v[74:77], v[36:39]
	s_waitcnt vmcnt(25)
	v_mfma_f32_16x16x32_bf16 v[32:35], v[106:109], v[74:77], v[32:35]
	s_waitcnt vmcnt(24)
	v_mfma_f32_16x16x32_bf16 v[28:31], v[110:113], v[74:77], v[28:31]
	s_waitcnt vmcnt(23)
	v_mfma_f32_16x16x32_bf16 v[24:27], v[114:117], v[74:77], v[24:27]
	s_waitcnt vmcnt(22)
	v_mfma_f32_16x16x32_bf16 v[20:23], v[118:121], v[74:77], v[20:23]
	s_waitcnt vmcnt(21)
	v_mfma_f32_16x16x32_bf16 v[16:19], v[122:125], v[74:77], v[16:19]
	s_waitcnt vmcnt(20)
	v_mfma_f32_16x16x32_bf16 v[12:15], v[126:129], v[74:77], v[12:15]
	s_waitcnt vmcnt(19)
	v_mfma_f32_16x16x32_bf16 v[8:11], v[130:133], v[74:77], v[8:11]
	s_waitcnt vmcnt(18)
	v_mfma_f32_16x16x32_bf16 v[4:7], v[134:137], v[74:77], v[4:7]
	s_waitcnt vmcnt(17)
	v_mfma_f32_16x16x32_bf16 v[0:3], v[138:141], v[74:77], v[0:3]
	s_cmp_eq_u32 s101, 0
	s_cbranch_scc1 .Ltl_lastB
; #define SCHED __builtin_amdgcn_sched_barrier(0)
; template <class Epi>
; DEV void skinny_item(LAS unsigned char* lds, const bf16_t* __restrict__ A, int lda, const bf16_t* __restrict__ B, int ldb, int K, int mb, int pn, const Epi& epi) {
;     ...
;     for (int st = wid; st < nsteps; st += 8) {
;         const int k0 = st * 32;
;         const bf16x8 a = *(const bf16x8*)(ap + k0);
;         bf16x8 b[16];
; #pragma unroll
;         for (int nb = 0; nb < 16; ++nb) b[nb] = *(const bf16x8*)(bp + nb * b16 + k0);
;         SCHED;
; #pragma unroll
;         for (int nb = 0; nb < 16; ++nb) acc[nb] = __builtin_amdgcn_mfma_f32_16x16x32_bf16(b[nb], a, acc[nb], 0, 0, 0);
;         SCHED;
;     }
	s_sub_u32 s101, s101, 1
	v_add_u32_e32 v68, 0x100, v68
	v_ashrrev_i32_e32 v69, 31, v68
	v_lshlrev_b64 v[74:75], 1, v[68:69]
	v_lshl_add_u64 v[138:139], v[64:65], 0, v[74:75]
	v_add_co_u32_e32 v82, vcc, s28, v138
	v_lshl_add_u64 v[76:77], v[66:67], 0, v[74:75]
	s_nop 0
	v_addc_co_u32_e32 v83, vcc, 0, v139, vcc
	v_add_co_u32_e32 v86, vcc, s29, v138
	global_load_dwordx4 v[74:77], v[76:77], off
	s_nop 0
	global_load_dwordx4 v[78:81], v[138:139], off
	v_addc_co_u32_e32 v87, vcc, 0, v139, vcc
	v_add_co_u32_e32 v90, vcc, s30, v138
	global_load_dwordx4 v[82:85], v[82:83], off
	s_nop 0
	global_load_dwordx4 v[86:89], v[86:87], off
	v_addc_co_u32_e32 v91, vcc, 0, v139, vcc
	v_add_co_u32_e32 v94, vcc, s19, v138
	s_nop 1
	v_addc_co_u32_e32 v95, vcc, 0, v139, vcc
	v_add_co_u32_e32 v98, vcc, s31, v138
	global_load_dwordx4 v[90:93], v[90:91], off
	s_nop 0
	global_load_dwordx4 v[94:97], v[94:95], off
	v_addc_co_u32_e32 v99, vcc, 0, v139, vcc
	v_add_co_u32_e32 v102, vcc, s34, v138
	s_nop 1
	v_addc_co_u32_e32 v103, vcc, 0, v139, vcc
	v_add_co_u32_e32 v106, vcc, s36, v138
	global_load_dwordx4 v[98:101], v[98:99], off
	s_nop 0
	global_load_dwordx4 v[102:105], v[102:103], off
	v_addc_co_u32_e32 v107, vcc, 0, v139, vcc
	v_add_co_u32_e32 v110, vcc, s37, v138
	s_nop 1
	v_addc_co_u32_e32 v111, vcc, 0, v139, vcc
	v_add_co_u32_e32 v114, vcc, s85, v138
	global_load_dwordx4 v[106:109], v[106:107], off
	s_nop 0
	global_load_dwordx4 v[110:113], v[110:111], off
	v_addc_co_u32_e32 v115, vcc, 0, v139, vcc
	v_add_co_u32_e32 v118, vcc, s78, v138
	s_nop 1
	v_addc_co_u32_e32 v119, vcc, 0, v139, vcc
	v_add_co_u32_e32 v122, vcc, s79, v138
	global_load_dwordx4 v[114:117], v[114:115], off
	s_nop 0
	global_load_dwordx4 v[118:121], v[118:119], off
	v_addc_co_u32_e32 v123, vcc, 0, v139, vcc
	v_add_co_u32_e32 v126, vcc, s90, v138
	s_nop 1
	v_addc_co_u32_e32 v127, vcc, 0, v139, vcc
	v_add_co_u32_e32 v130, vcc, s91, v138
	global_load_dwordx4 v[122:125], v[122:123], off
	s_nop 0
	global_load_dwordx4 v[126:129], v[126:127], off
	v_addc_co_u32_e32 v131, vcc, 0, v139, vcc
	v_add_co_u32_e32 v134, vcc, s60, v138
	s_nop 1
	v_addc_co_u32_e32 v135, vcc, 0, v139, vcc
	v_add_co_u32_e32 v138, vcc, s61, v138
	global_load_dwordx4 v[130:133], v[130:131], off
	s_nop 0
	global_load_dwordx4 v[134:137], v[134:135], off
	v_addc_co_u32_e32 v139, vcc, 0, v139, vcc
	global_load_dwordx4 v[138:141], v[138:139], off
	s_waitcnt vmcnt(32)
	v_mfma_f32_16x16x32_bf16 v[60:63], v[146:149], v[142:145], v[60:63]
	s_waitcnt vmcnt(31)
	v_mfma_f32_16x16x32_bf16 v[56:59], v[150:153], v[142:145], v[56:59]
	s_waitcnt vmcnt(30)
	v_mfma_f32_16x16x32_bf16 v[52:55], v[154:157], v[142:145], v[52:55]
	s_waitcnt vmcnt(29)
	v_mfma_f32_16x16x32_bf16 v[48:51], v[158:161], v[142:145], v[48:51]
	s_waitcnt vmcnt(28)
	v_mfma_f32_16x16x32_bf16 v[44:47], v[162:165], v[142:145], v[44:47]
	s_waitcnt vmcnt(27)
	v_mfma_f32_16x16x32_bf16 v[40:43], v[166:169], v[142:145], v[40:43]
	s_waitcnt vmcnt(26)
	v_mfma_f32_16x16x32_bf16 v[36:39], v[170:173], v[142:145], v[36:39]
	s_waitcnt vmcnt(25)
	v_mfma_f32_16x16x32_bf16 v[32:35], v[174:177], v[142:145], v[32:35]
	s_waitcnt vmcnt(24)
	v_mfma_f32_16x16x32_bf16 v[28:31], v[178:181], v[142:145], v[28:31]
	s_waitcnt vmcnt(23)
	v_mfma_f32_16x16x32_bf16 v[24:27], v[182:185], v[142:145], v[24:27]
	s_waitcnt vmcnt(22)
	v_mfma_f32_16x16x32_bf16 v[20:23], v[212:215], v[142:145], v[20:23]
	s_waitcnt vmcnt(21)
	v_mfma_f32_16x16x32_bf16 v[16:19], v[216:219], v[142:145], v[16:19]
	s_waitcnt vmcnt(20)
	v_mfma_f32_16x16x32_bf16 v[12:15], v[220:223], v[142:145], v[12:15]
	s_waitcnt vmcnt(19)
	v_mfma_f32_16x16x32_bf16 v[8:11], v[224:227], v[142:145], v[8:11]
	s_waitcnt vmcnt(18)
	v_mfma_f32_16x16x32_bf16 v[4:7], v[228:231], v[142:145], v[4:7]
	s_waitcnt vmcnt(17)
	v_mfma_f32_16x16x32_bf16 v[0:3], v[232:235], v[142:145], v[0:3]
	s_branch .Ltl_loop
.Ltl_lastA:
	s_waitcnt vmcnt(15)
	v_mfma_f32_16x16x32_bf16 v[60:63], v[78:81], v[74:77], v[60:63]
	s_waitcnt vmcnt(14)
	v_mfma_f32_16x16x32_bf16 v[56:59], v[82:85], v[74:77], v[56:59]
	s_waitcnt vmcnt(13)
	v_mfma_f32_16x16x32_bf16 v[52:55], v[86:89], v[74:77], v[52:55]
	s_waitcnt vmcnt(12)
	v_mfma_f32_16x16x32_bf16 v[48:51], v[90:93], v[74:77], v[48:51]
	s_waitcnt vmcnt(11)
	v_mfma_f32_16x16x32_bf16 v[44:47], v[94:97], v[74:77], v[44:47]
	s_waitcnt vmcnt(10)
	v_mfma_f32_16x16x32_bf16 v[40:43], v[98:101], v[74:77], v[40:43]
	s_waitcnt vmcnt(9)
	v_mfma_f32_16x16x32_bf16 v[36:39], v[102:105], v[74:77], v[36:39]
	s_waitcnt vmcnt(8)
	v_mfma_f32_16x16x32_bf16 v[32:35], v[106:109], v[74:77], v[32:35]
	s_waitcnt vmcnt(7)
	v_mfma_f32_16x16x32_bf16 v[28:31], v[110:113], v[74:77], v[28:31]
	s_waitcnt vmcnt(6)
	v_mfma_f32_16x16x32_bf16 v[24:27], v[114:117], v[74:77], v[24:27]
	s_waitcnt vmcnt(5)
	v_mfma_f32_16x16x32_bf16 v[20:23], v[118:121], v[74:77], v[20:23]
	s_waitcnt vmcnt(4)
	v_mfma_f32_16x16x32_bf16 v[16:19], v[122:125], v[74:77], v[16:19]
	s_waitcnt vmcnt(3)
	v_mfma_f32_16x16x32_bf16 v[12:15], v[126:129], v[74:77], v[12:15]
	s_waitcnt vmcnt(2)
	v_mfma_f32_16x16x32_bf16 v[8:11], v[130:133], v[74:77], v[8:11]
	s_waitcnt vmcnt(1)
	v_mfma_f32_16x16x32_bf16 v[4:7], v[134:137], v[74:77], v[4:7]
	s_waitcnt vmcnt(0)
	v_mfma_f32_16x16x32_bf16 v[0:3], v[138:141], v[74:77], v[0:3]
	s_branch .Ltl_done
; #define LAS __attribute__((address_space(3)))
; DEV unsigned cvt_pk_bf16(float lo, float hi) { unsigned r; asm("v_cvt_pk_bf16_f32 %0, %1, %2" : "=v"(r) : "v"(lo), "v"(hi)); return r; }
; DEV float bflo(unsigned w) { return __uint_as_float(w << 16); }
; DEV float bfhi(unsigned w) { return __uint_as_float(w & 0xffff0000u); }
; DEV void skinny_reduce(LAS unsigned char* lds, int wid, int lane, const f32x4 (&acc)[16], f32x4& a0, f32x4& a1) {
; #pragma unroll
;     for (int nb = 0; nb < 16; ++nb) *(LAS f32x4*)(lds + ((wid * 16 + nb) * 64 + lane) * 16) = acc[nb];
;     __syncthreads();
;     a0 = (f32x4){0.f, 0.f, 0.f, 0.f}; a1 = a0;
; #pragma unroll
;     for (int w = 0; w < 8; ++w) { a0 += *(const LAS f32x4*)(lds + ((w * 16 + 2 * wid) * 64 + lane) * 16); a1 += *(const LAS f32x4*)(lds + ((w * 16 + 2 * wid + 1) * 64 + lane) * 16); }
;     __syncthreads();
;     DEV void skinny(f32x4 a0, f32x4 a1, int mb, int pn, LAS unsigned char* lds) const {
;         EPI_IDS
;         const int row = TX + mb * 16 + fr, col = pn * 256 + wid * 32 + fq * 4;
;         bf16_t* bp = hb + (size_t)row * D + col;
;         const u32x2 r0 = *(const u32x2*)bp, r1 = *(const u32x2*)(bp + 16);
;         f32x4 v0 = a0, v1 = a1;
;         v0[0] += bflo(r0.x); v0[1] += bfhi(r0.x); v0[2] += bflo(r0.y); v0[3] += bfhi(r0.y);
;         v1[0] += bflo(r1.x); v1[1] += bfhi(r1.x); v1[2] += bflo(r1.y); v1[3] += bfhi(r1.y);
;         *(u32x2*)bp = (u32x2){cvt_pk_bf16(v0[0], v0[1]), cvt_pk_bf16(v0[2], v0[3])};
;         *(u32x2*)(bp + 16) = (u32x2){cvt_pk_bf16(v1[0], v1[1]), cvt_pk_bf16(v1[2], v1[3])};
;         float s = ((v0[0] * v0[0] + v0[1] * v0[1]) + (v0[2] * v0[2] + v0[3] * v0[3])) + ((v1[0] * v1[0] + v1[1] * v1[1]) + (v1[2] * v1[2] + v1[3] * v1[3]));
;         s += __shfl_xor(s, 16); s += __shfl_xor(s, 32);
;         LAS float* ex = (LAS float*)(lds + LDS_EX);
;         if (fq == 0) ex[fr * 8 + wid] = s;
.Ltl_lastB:
	s_waitcnt vmcnt(15)
	v_mfma_f32_16x16x32_bf16 v[60:63], v[146:149], v[142:145], v[60:63]
	s_waitcnt vmcnt(14)
	v_mfma_f32_16x16x32_bf16 v[56:59], v[150:153], v[142:145], v[56:59]
	s_waitcnt vmcnt(13)
	v_mfma_f32_16x16x32_bf16 v[52:55], v[154:157], v[142:145], v[52:55]
	s_waitcnt vmcnt(12)
	v_mfma_f32_16x16x32_bf16 v[48:51], v[158:161], v[142:145], v[48:51]
	s_waitcnt vmcnt(11)
	v_mfma_f32_16x16x32_bf16 v[44:47], v[162:165], v[142:145], v[44:47]
	s_waitcnt vmcnt(10)
	v_mfma_f32_16x16x32_bf16 v[40:43], v[166:169], v[142:145], v[40:43]
	s_waitcnt vmcnt(9)
	v_mfma_f32_16x16x32_bf16 v[36:39], v[170:173], v[142:145], v[36:39]
	s_waitcnt vmcnt(8)
	v_mfma_f32_16x16x32_bf16 v[32:35], v[174:177], v[142:145], v[32:35]
	s_waitcnt vmcnt(7)
	v_mfma_f32_16x16x32_bf16 v[28:31], v[178:181], v[142:145], v[28:31]
	s_waitcnt vmcnt(6)
	v_mfma_f32_16x16x32_bf16 v[24:27], v[182:185], v[142:145], v[24:27]
	s_waitcnt vmcnt(5)
	v_mfma_f32_16x16x32_bf16 v[20:23], v[212:215], v[142:145], v[20:23]
	s_waitcnt vmcnt(4)
	v_mfma_f32_16x16x32_bf16 v[16:19], v[216:219], v[142:145], v[16:19]
	s_waitcnt vmcnt(3)
	v_mfma_f32_16x16x32_bf16 v[12:15], v[220:223], v[142:145], v[12:15]
	s_waitcnt vmcnt(2)
	v_mfma_f32_16x16x32_bf16 v[8:11], v[224:227], v[142:145], v[8:11]
	s_waitcnt vmcnt(1)
	v_mfma_f32_16x16x32_bf16 v[4:7], v[228:231], v[142:145], v[4:7]
	s_waitcnt vmcnt(0)
	v_mfma_f32_16x16x32_bf16 v[0:3], v[232:235], v[142:145], v[0:3]
.Ltl_done:
	s_or_b64 exec, exec, s[8:9]
.LBB0_1367:
	s_or_b64 exec, exec, s[0:1]
	v_lshlrev_b32_e32 v65, 4, v71
	v_lshlrev_b32_e32 v64, 14, v70
	v_and_b32_e32 v65, 0x3f0, v65
	v_add3_u32 v64, 0, v64, v65
	ds_write_b128 v64, v[60:63]
	ds_write_b128 v64, v[56:59] offset:1024
	ds_write_b128 v64, v[52:55] offset:2048
	ds_write_b128 v64, v[48:51] offset:3072
	ds_write_b128 v64, v[44:47] offset:4096
	ds_write_b128 v64, v[40:43] offset:5120
	ds_write_b128 v64, v[36:39] offset:6144
	ds_write_b128 v64, v[32:35] offset:7168
	ds_write_b128 v64, v[28:31] offset:8192
	ds_write_b128 v64, v[24:27] offset:9216
	ds_write_b128 v64, v[20:23] offset:10240
	ds_write_b128 v64, v[16:19] offset:11264
	ds_write_b128 v64, v[12:15] offset:12288
	ds_write_b128 v64, v[8:11] offset:13312
	ds_write_b128 v64, v[4:7] offset:14336
	ds_write_b128 v64, v[0:3] offset:15360
	v_lshlrev_b32_e32 v0, 11, v70
	v_add3_u32 v12, 0, v0, v65
	s_waitcnt lgkmcnt(0)
	s_barrier
	ds_read_b128 v[0:3], v12
	v_readlane_b32 s0, v254, 31
	s_waitcnt lgkmcnt(0)
	v_pk_add_f32 v[4:5], v[2:3], 0 op_sel_hi:[1,0]
	v_pk_add_f32 v[6:7], v[0:1], 0 op_sel_hi:[1,0]
	ds_read_b128 v[0:3], v12 offset:1024
	s_waitcnt lgkmcnt(0)
	v_pk_add_f32 v[8:9], v[2:3], 0 op_sel_hi:[1,0]
	v_pk_add_f32 v[10:11], v[0:1], 0 op_sel_hi:[1,0]
	ds_read_b128 v[0:3], v12 offset:16384
	s_waitcnt lgkmcnt(0)
	v_pk_add_f32 v[4:5], v[4:5], v[2:3]
	v_pk_add_f32 v[6:7], v[6:7], v[0:1]
	ds_read_b128 v[0:3], v12 offset:17408
	s_waitcnt lgkmcnt(0)
	v_pk_add_f32 v[8:9], v[8:9], v[2:3]
	v_pk_add_f32 v[10:11], v[10:11], v[0:1]
	ds_read_b128 v[0:3], v12 offset:32768
	s_waitcnt lgkmcnt(0)
	v_pk_add_f32 v[4:5], v[4:5], v[2:3]
	v_pk_add_f32 v[6:7], v[6:7], v[0:1]
	ds_read_b128 v[0:3], v12 offset:33792
	s_waitcnt lgkmcnt(0)
	v_pk_add_f32 v[8:9], v[8:9], v[2:3]
	v_pk_add_f32 v[10:11], v[10:11], v[0:1]
	ds_read_b128 v[0:3], v12 offset:49152
	s_waitcnt lgkmcnt(0)
	v_pk_add_f32 v[4:5], v[4:5], v[2:3]
	v_pk_add_f32 v[6:7], v[6:7], v[0:1]
	ds_read_b128 v[0:3], v12 offset:50176
	s_waitcnt lgkmcnt(0)
	v_pk_add_f32 v[10:11], v[10:11], v[0:1]
	v_add_u32_e32 v0, 0x10000, v12
	v_pk_add_f32 v[8:9], v[8:9], v[2:3]
	ds_read_b128 v[0:3], v0
	s_waitcnt lgkmcnt(0)
	v_pk_add_f32 v[6:7], v[6:7], v[0:1]
	v_add_u32_e32 v0, 0x10400, v12
	v_pk_add_f32 v[4:5], v[4:5], v[2:3]
	ds_read_b128 v[0:3], v0
	s_waitcnt lgkmcnt(0)
	v_pk_add_f32 v[10:11], v[10:11], v[0:1]
	v_add_u32_e32 v0, 0x14000, v12
	v_pk_add_f32 v[8:9], v[8:9], v[2:3]
	ds_read_b128 v[0:3], v0
	s_waitcnt lgkmcnt(0)
	v_pk_add_f32 v[6:7], v[6:7], v[0:1]
	v_add_u32_e32 v0, 0x14400, v12
	v_pk_add_f32 v[4:5], v[4:5], v[2:3]
	ds_read_b128 v[0:3], v0
	s_waitcnt lgkmcnt(0)
	v_pk_add_f32 v[10:11], v[10:11], v[0:1]
	v_add_u32_e32 v0, 0x18000, v12
	v_pk_add_f32 v[8:9], v[8:9], v[2:3]
	ds_read_b128 v[0:3], v0
	s_waitcnt lgkmcnt(0)
	v_pk_add_f32 v[6:7], v[6:7], v[0:1]
	v_add_u32_e32 v0, 0x18400, v12
	v_pk_add_f32 v[4:5], v[4:5], v[2:3]
	ds_read_b128 v[0:3], v0
	s_waitcnt lgkmcnt(0)
	v_pk_add_f32 v[10:11], v[10:11], v[0:1]
	v_add_u32_e32 v0, 0x1c000, v12
	v_pk_add_f32 v[8:9], v[8:9], v[2:3]
	ds_read_b128 v[0:3], v0
	s_waitcnt lgkmcnt(0)
	v_pk_add_f32 v[6:7], v[6:7], v[0:1]
	v_add_u32_e32 v0, 0x1c400, v12
	v_pk_add_f32 v[4:5], v[4:5], v[2:3]
	ds_read_b128 v[0:3], v0
	s_waitcnt lgkmcnt(0)
	s_barrier
	v_pk_add_f32 v[10:11], v[10:11], v[0:1]
	v_mov_b32_e32 v0, v188
	v_pk_add_f32 v[8:9], v[8:9], v[2:3]
	s_nop 0
	v_and_b32_e32 v2, 15, v0
	v_ashrrev_i32_e32 v1, 6, v0
	v_or_b32_e32 v3, s0, v2
	v_readlane_b32 s0, v254, 32
	v_bfe_u32 v18, v0, 4, 2
	v_lshlrev_b32_e32 v194, 11, v3
	v_lshl_add_u32 v12, v1, 5, s0
	v_lshl_or_b32 v12, v18, 2, v12
	v_lshl_add_u64 v[14:15], s[72:73], 0, v[194:195]
	v_ashrrev_i32_e32 v13, 31, v12
	v_lshl_add_u64 v[12:13], v[12:13], 1, v[14:15]
	global_load_dwordx2 v[14:15], v[12:13], off
	global_load_dwordx2 v[16:17], v[12:13], off offset:32
	s_waitcnt vmcnt(1)
	v_lshlrev_b32_e32 v3, 16, v14
	v_add_f32_e32 v3, v6, v3
	v_and_b32_e32 v6, 0xffff0000, v14
	v_add_f32_e32 v6, v7, v6
	v_lshlrev_b32_e32 v7, 16, v15
	v_add_f32_e32 v7, v4, v7
	v_and_b32_e32 v4, 0xffff0000, v15
	v_add_f32_e32 v14, v5, v4
	s_waitcnt vmcnt(0)
	v_lshlrev_b32_e32 v4, 16, v16
	v_add_f32_e32 v10, v10, v4
	v_and_b32_e32 v4, 0xffff0000, v16
	v_add_f32_e32 v11, v11, v4
	v_lshlrev_b32_e32 v4, 16, v17
	v_add_f32_e32 v8, v8, v4
	v_and_b32_e32 v4, 0xffff0000, v17
	v_add_f32_e32 v9, v9, v4
	v_cvt_pk_bf16_f32 v4, v3, v6
	v_cvt_pk_bf16_f32 v5, v7, v14
	global_store_dwordx2 v[12:13], v[4:5], off
	v_cvt_pk_bf16_f32 v4, v10, v11
	v_cvt_pk_bf16_f32 v5, v8, v9
	global_store_dwordx2 v[12:13], v[4:5], off offset:32
	v_mul_f32_e32 v4, v6, v6
	v_fmac_f32_e32 v4, v3, v3
	v_mul_f32_e32 v3, v14, v14
	v_fmac_f32_e32 v3, v7, v7
	v_add_f32_e32 v3, v4, v3
	v_mul_f32_e32 v4, v11, v11
	v_mul_f32_e32 v5, v9, v9
	v_fmac_f32_e32 v4, v10, v10
	v_fmac_f32_e32 v5, v8, v8
	v_add_f32_e32 v4, v4, v5
	v_and_b32_e32 v5, 64, v207
	v_add_f32_e32 v3, v3, v4
	v_xor_b32_e32 v4, 16, v207
	v_add_u32_e32 v5, 64, v5
	v_cmp_lt_i32_e32 vcc, v4, v5
	s_nop 1
	v_cndmask_b32_e32 v4, v207, v4, vcc
	v_lshlrev_b32_e32 v4, 2, v4
	ds_bpermute_b32 v4, v4, v3
	s_waitcnt lgkmcnt(0)
	v_add_f32_e32 v3, v3, v4
	v_xor_b32_e32 v4, 32, v207
	v_cmp_lt_i32_e32 vcc, v4, v5
	s_nop 1
	v_cndmask_b32_e32 v4, v207, v4, vcc
	v_lshlrev_b32_e32 v4, 2, v4
	ds_bpermute_b32 v4, v4, v3
	v_cmp_eq_u32_e32 vcc, 0, v18
	s_and_saveexec_b64 s[0:1], vcc
	s_cbranch_execz .LBB0_1369
	v_lshlrev_b32_e32 v2, 5, v2
	s_add_i32 s8, 0, 0x20000
	v_lshlrev_b32_e32 v1, 2, v1
	s_waitcnt lgkmcnt(0)
	v_add_f32_e32 v3, v3, v4
	v_add3_u32 v1, s8, v2, v1
	ds_write_b32 v1, v3
